# indexer passes 0/1: hand-written straight-line scoring + histogram update per 64-key group
# speedup vs baseline: 1.0197x; 1.0197x over previous
; DI f32x4 mfma16(bf16x8 a, bf16x8 b, f32x4 c) { return __builtin_amdgcn_mfma_f32_16x16x32_bf16(a, b, c, 0, 0, 0); }
; DI float relu_(float x) { return __builtin_amdgcn_fmed3f(x, 0.f, __builtin_inff()); }
; DI void dsa_task(const Params& p, int l, int isP, int b, int tq, char* smem, const bool dry) {
;     ...
;           for (int tt = 0; tt < 4; tt++) {
;             const bf16_t* br = kst + ((tg * 4 + tt) * 16 + cl) * 72 + g4 * 8;
;             const bf16x8 b0 = *(const bf16x8*)br;
;             const bf16x8 b1 = *(const bf16x8*)(br + 32);
;             f32x4 a = (f32x4){0.f, 0.f, 0.f, 0.f};
;             a = mfma16(aq0, b0, a);
;             a = mfma16(aq1, b1, a);
;             const float score = wq.x * relu_(a[0]) + wq.y * relu_(a[1]) + wq.z * relu_(a[2]) + wq.w * relu_(a[3]);
;             keys[tt] = mono_key(score);
;           }
; #pragma unroll
;           for (int tt = 0; tt < 4; tt++) {
;             const unsigned key = keys[tt];
;             const int kidx = kc * 256 + (tg * 4 + tt) * 16 + cl;
;             if (kind == 0) {
;               const bool match = (pass == 0) || ((key >> (shift + 8)) == prefix);
;               if (match) atomicAdd(&hist[qloc * 256 + ((key >> shift) & 255u)], 1u);
.Lidx_k0:
	s_nop 1
	v_max_f32_e32 v224, 0, v60
	v_max_f32_e32 v228, 0, v56
	v_max_f32_e32 v225, 0, v61
	v_max_f32_e32 v229, 0, v57
	v_max_f32_e32 v226, 0, v62
	v_max_f32_e32 v230, 0, v58
	v_max_f32_e32 v227, 0, v63
	v_max_f32_e32 v231, 0, v59
	v_mul_f32_e32 v225, v13, v225
	v_mul_f32_e32 v229, v13, v229
	v_fmac_f32_e32 v225, v12, v224
	v_fmac_f32_e32 v229, v12, v228
	v_fmac_f32_e32 v225, v14, v226
	v_fmac_f32_e32 v229, v14, v230
	v_fmac_f32_e32 v225, v15, v227
	v_fmac_f32_e32 v229, v15, v231
	v_add_f32_e32 v224, 0, v225
	v_add_f32_e32 v228, 0, v229
	v_ashrrev_i32_e32 v225, 31, v224
	v_ashrrev_i32_e32 v229, 31, v228
	v_bitop3_b32 v226, v225, v224, s71 bitop3:0x36
	v_bitop3_b32 v230, v229, v228, s71 bitop3:0x36
	v_lshrrev_b32_e32 v224, s95, v226
	v_lshrrev_b32_e32 v228, s95, v230
	v_bfe_u32 v227, v226, s48, 8
	v_bfe_u32 v231, v230, s48, 8
	v_lshl_add_u32 v227, v227, 2, v91
	v_lshl_add_u32 v231, v231, 2, v91
	v_cmp_eq_u32_e32 vcc, v224, v101
	s_or_b64 s[40:41], s[96:97], vcc
	s_and_saveexec_b64 s[38:39], s[40:41]
	ds_add_u32 v227, v185
	s_or_b64 exec, exec, s[38:39]
	v_cmp_eq_u32_e32 vcc, v228, v101
	s_or_b64 s[40:41], s[96:97], vcc
	s_and_saveexec_b64 s[38:39], s[40:41]
	ds_add_u32 v231, v185
	s_or_b64 exec, exec, s[38:39]
	v_max_f32_e32 v232, 0, v52
	v_max_f32_e32 v236, 0, v48
	v_max_f32_e32 v233, 0, v53
	v_max_f32_e32 v237, 0, v49
	v_max_f32_e32 v234, 0, v54
	v_max_f32_e32 v238, 0, v50
	v_max_f32_e32 v235, 0, v55
	v_max_f32_e32 v239, 0, v51
	v_mul_f32_e32 v233, v13, v233
	v_mul_f32_e32 v237, v13, v237
	v_fmac_f32_e32 v233, v12, v232
	v_fmac_f32_e32 v237, v12, v236
	v_fmac_f32_e32 v233, v14, v234
	v_fmac_f32_e32 v237, v14, v238
	v_fmac_f32_e32 v233, v15, v235
	v_fmac_f32_e32 v237, v15, v239
	v_add_f32_e32 v232, 0, v233
	v_add_f32_e32 v236, 0, v237
	v_ashrrev_i32_e32 v233, 31, v232
	v_ashrrev_i32_e32 v237, 31, v236
	v_bitop3_b32 v234, v233, v232, s71 bitop3:0x36
	v_bitop3_b32 v238, v237, v236, s71 bitop3:0x36
	v_lshrrev_b32_e32 v232, s95, v234
	v_lshrrev_b32_e32 v236, s95, v238
	v_bfe_u32 v235, v234, s48, 8
	v_bfe_u32 v239, v238, s48, 8
	v_lshl_add_u32 v235, v235, 2, v91
	v_lshl_add_u32 v239, v239, 2, v91
	v_cmp_eq_u32_e32 vcc, v232, v101
	s_or_b64 s[40:41], s[96:97], vcc
	s_and_saveexec_b64 s[38:39], s[40:41]
	ds_add_u32 v235, v185
	s_or_b64 exec, exec, s[38:39]
	v_cmp_eq_u32_e32 vcc, v236, v101
	s_or_b64 s[40:41], s[96:97], vcc
	s_and_saveexec_b64 s[38:39], s[40:41]
	ds_add_u32 v239, v185
	s_or_b64 exec, exec, s[38:39]
	s_branch .LBB0_1310

; DI f32x4 mfma16(bf16x8 a, bf16x8 b, f32x4 c) { return __builtin_amdgcn_mfma_f32_16x16x32_bf16(a, b, c, 0, 0, 0); }
; DI float relu_(float x) { return __builtin_amdgcn_fmed3f(x, 0.f, __builtin_inff()); }
; DI void dsa_task(const Params& p, int l, int isP, int b, int tq, char* smem, const bool dry) {
;     ...
;         for (int tg = 0; tg < ngrp; tg++) {
;           unsigned keys[4];
; #pragma unroll
;           for (int tt = 0; tt < 4; tt++) {
;             const bf16_t* br = kst + ((tg * 4 + tt) * 16 + cl) * 72 + g4 * 8;
;             const bf16x8 b0 = *(const bf16x8*)br;
;             const bf16x8 b1 = *(const bf16x8*)(br + 32);
;             f32x4 a = (f32x4){0.f, 0.f, 0.f, 0.f};
;             a = mfma16(aq0, b0, a);
;             a = mfma16(aq1, b1, a);
;             const float score = wq.x * relu_(a[0]) + wq.y * relu_(a[1]) + wq.z * relu_(a[2]) + wq.w * relu_(a[3]);
;             keys[tt] = mono_key(score);
;           }
.LBB0_1311:
	ds_read_b128 v[224:227], v123
	ds_read_b128 v[228:231], v123 offset:64
	ds_read_b128 v[232:235], v123 offset:2304
	ds_read_b128 v[236:239], v123 offset:2368
	ds_read_b128 v[240:243], v123 offset:4608
	ds_read_b128 v[244:247], v123 offset:4672
	ds_read_b128 v[248:251], v123 offset:6912
	ds_read_b128 v[124:127], v123 offset:6976
	s_cmp_lt_i32 s76, 5
	s_waitcnt lgkmcnt(7)
	v_mfma_f32_16x16x32_bf16 v[60:63], v[4:7], v[224:227], 0
	s_waitcnt lgkmcnt(5)
	v_mfma_f32_16x16x32_bf16 v[56:59], v[4:7], v[232:235], 0
	s_waitcnt lgkmcnt(3)
	v_mfma_f32_16x16x32_bf16 v[52:55], v[4:7], v[240:243], 0
	s_waitcnt lgkmcnt(1)
	v_mfma_f32_16x16x32_bf16 v[48:51], v[4:7], v[248:251], 0
	v_mfma_f32_16x16x32_bf16 v[60:63], v[8:11], v[228:231], v[60:63]
	v_mfma_f32_16x16x32_bf16 v[56:59], v[8:11], v[236:239], v[56:59]
	v_mfma_f32_16x16x32_bf16 v[52:55], v[8:11], v[244:247], v[52:55]
	s_waitcnt lgkmcnt(0)
	v_mfma_f32_16x16x32_bf16 v[48:51], v[8:11], v[124:127], v[48:51]
	s_cmp_lt_u32 s76, 2
	s_cbranch_scc1 .Lidx_k0
	s_cmp_lt_i32 s76, 5
	s_cbranch_scc1 .LBB0_1313
	s_cmp_lg_u32 s76, 5
	s_mov_b64 s[38:39], -1
	s_cselect_b64 s[40:41], -1, 0
	s_cbranch_execz .LBB0_1314
	s_branch .LBB0_1315
